# SwiGLU epilogue rows software-pipelined: exp/rcp interleaved one-by-one with the neighbouring rows' ordinary VALU ops (same math and registers as before)
# baseline (speedup 1.0000x reference)
; __device__ __forceinline__ unsigned cvt_pk_bf16(float lo, float hi) { unsigned r; asm volatile("v_cvt_pk_bf16_f32 %0, %1, %2" : "=v"(r) : "v"(lo), "v"(hi)); return r; }
; #define LAS __attribute__((address_space(3)))
; __device__ __forceinline__ float fast_sigmoid(float x) { return __builtin_amdgcn_rcpf(1.0f + __expf(-x)); }
;     __device__ __forceinline__ void operator()(const f32x4 (&acc)[2][2][4][2], const pg8::Unit& u, int wr, int wc, int fr_, int fq_, LAS const unsigned char* xl) const {
;     ...
;                 for (int m = 0; m < 4; ++m) { const f32x4 pv = *(LAS const f32x4*)(xl + (ai * 128 + wr * 64 + m * 16 + fr) * 64 + fq * 16); rv[ai][m] = (pv[0] + pv[1]) + (pv[2] + pv[3]); }
; #pragma unroll
;             for (int ai = 0; ai < 2; ++ai)
; #pragma unroll
;                 for (int m = 0; m < 4; ++m) rv[ai][m] = __builtin_amdgcn_rsqf(xrow16_sum(rv[ai][m]) * (1.0f / 1024.0f) + EPS);
;     ...
;                         bf16_t* rowp = O + (size_t)row * ldc + u.pn * 128 + wc * 32 + 8 * fq;
;                         float a[8];
; #pragma unroll
;                         for (int n = 0; n < 2; ++n)
; #pragma unroll
;                             for (int j = 0; j < 4; ++j) { const float g = acc[ai][0][m][n][j] * rinv, up = acc[ai][1][m][n][j] * rinv; a[4 * n + j] = g * fast_sigmoid(g) * up; }
;                         u32x4 w; w.x = pg8::cvt_pk_bf16(a[0], a[1]); w.y = pg8::cvt_pk_bf16(a[2], a[3]); w.z = pg8::cvt_pk_bf16(a[4], a[5]); w.w = pg8::cvt_pk_bf16(a[6], a[7]);
;                         *(u32x4*)rowp = w;
.LBB0_425:
	s_and_b64 vcc, exec, s[6:7]
	v_add_u32_e32 v135, s48, v237
	v_lshlrev_b32_e32 v128, 4, v238
	v_lshlrev_b32_e32 v129, 6, v135
	s_mov_b32 s1, 0x20000
	v_add3_u32 v132, s1, v128, v129
	ds_read_b128 v[152:155], v132
	ds_read_b128 v[156:159], v132 offset:1024
	ds_read_b128 v[160:163], v132 offset:2048
	ds_read_b128 v[164:167], v132 offset:3072
	ds_read_b128 v[168:171], v132 offset:8192
	ds_read_b128 v[172:175], v132 offset:9216
	ds_read_b128 v[176:179], v132 offset:10240
	ds_read_b128 v[180:183], v132 offset:11264
	v_lshl_add_u32 v129, s0, 8, v135
	v_mov_b64_e32 v[130:131], s[72:73]
	s_lshl_b32 s0, s2, 7
	v_mad_i64_i32 v[148:149], s[26:27], v129, s83, v[130:131]
	s_ashr_i32 s1, s0, 31
	s_lshl_b64 s[0:1], s[0:1], 1
	v_lshlrev_b32_e32 v146, 3, v238
	v_ashrrev_i32_e32 v147, 31, v146
	v_lshl_add_u64 v[148:149], v[148:149], 0, s[0:1]
	v_lshl_add_u64 v[148:149], v[148:149], 0, s[86:87]
	v_lshlrev_b64 v[146:147], 1, v[146:147]
	v_lshl_add_u64 v[148:149], v[148:149], 0, v[146:147]
	s_mov_b32 s100, 0x18000
	s_mov_b32 s101, 0
	s_mov_b32 s0, 0x78000
	s_mov_b32 s1, 0
	s_waitcnt lgkmcnt(0)
	v_add_f32_e32 v152, v152, v153
	v_add_f32_e32 v154, v154, v155
	v_add_f32_e32 v156, v156, v157
	v_add_f32_e32 v158, v158, v159
	v_add_f32_e32 v160, v160, v161
	v_add_f32_e32 v162, v162, v163
	v_add_f32_e32 v164, v164, v165
	v_add_f32_e32 v166, v166, v167
	v_add_f32_e32 v168, v168, v169
	v_add_f32_e32 v170, v170, v171
	v_add_f32_e32 v172, v172, v173
	v_add_f32_e32 v174, v174, v175
	v_add_f32_e32 v176, v176, v177
	v_add_f32_e32 v178, v178, v179
	v_add_f32_e32 v180, v180, v181
	v_add_f32_e32 v182, v182, v183
	v_add_f32_e32 v184, v152, v154
	v_add_f32_e32 v185, v156, v158
	v_add_f32_e32 v186, v160, v162
	v_add_f32_e32 v187, v164, v166
	v_add_f32_e32 v188, v168, v170
	v_add_f32_e32 v189, v172, v174
	v_add_f32_e32 v190, v176, v178
	v_add_f32_e32 v191, v180, v182
	v_mov_b32_e32 v152, v184
	v_mov_b32_e32 v153, v185
	v_mov_b32_e32 v154, v186
	v_mov_b32_e32 v155, v187
	v_mov_b32_e32 v156, v188
	v_mov_b32_e32 v157, v189
	v_mov_b32_e32 v158, v190
	v_mov_b32_e32 v159, v191
	v_permlane16_swap_b32_e32 v184, v152
	v_permlane16_swap_b32_e32 v185, v153
	v_permlane16_swap_b32_e32 v186, v154
	v_permlane16_swap_b32_e32 v187, v155
	v_permlane16_swap_b32_e32 v188, v156
	v_permlane16_swap_b32_e32 v189, v157
	v_permlane16_swap_b32_e32 v190, v158
	v_permlane16_swap_b32_e32 v191, v159
	v_add_f32_e32 v184, v184, v152
	v_add_f32_e32 v185, v185, v153
	v_add_f32_e32 v186, v186, v154
	v_add_f32_e32 v187, v187, v155
	v_add_f32_e32 v188, v188, v156
	v_add_f32_e32 v189, v189, v157
	v_add_f32_e32 v190, v190, v158
	v_add_f32_e32 v191, v191, v159
	v_mov_b32_e32 v152, v184
	v_mov_b32_e32 v153, v185
	v_mov_b32_e32 v154, v186
	v_mov_b32_e32 v155, v187
	v_mov_b32_e32 v156, v188
	v_mov_b32_e32 v157, v189
	v_mov_b32_e32 v158, v190
	v_mov_b32_e32 v159, v191
	v_permlane32_swap_b32_e32 v184, v152
	v_permlane32_swap_b32_e32 v185, v153
	v_permlane32_swap_b32_e32 v186, v154
	v_permlane32_swap_b32_e32 v187, v155
	v_permlane32_swap_b32_e32 v188, v156
	v_permlane32_swap_b32_e32 v189, v157
	v_permlane32_swap_b32_e32 v190, v158
	v_permlane32_swap_b32_e32 v191, v159
	v_add_f32_e32 v184, v184, v152
	v_add_f32_e32 v185, v185, v153
	v_add_f32_e32 v186, v186, v154
	v_add_f32_e32 v187, v187, v155
	v_add_f32_e32 v188, v188, v156
	v_add_f32_e32 v189, v189, v157
	v_add_f32_e32 v190, v190, v158
	v_add_f32_e32 v191, v191, v159
	v_fmamk_f32 v184, v184, 0x3a800000, v233
	v_fmamk_f32 v185, v185, 0x3a800000, v233
	v_fmamk_f32 v186, v186, 0x3a800000, v233
	v_fmamk_f32 v187, v187, 0x3a800000, v233
	v_fmamk_f32 v188, v188, 0x3a800000, v233
	v_fmamk_f32 v189, v189, 0x3a800000, v233
	v_fmamk_f32 v190, v190, 0x3a800000, v233
	v_fmamk_f32 v191, v191, 0x3a800000, v233
	v_rsq_f32_e32 v184, v184
	v_rsq_f32_e32 v185, v185
	v_rsq_f32_e32 v186, v186
	v_rsq_f32_e32 v187, v187
	v_rsq_f32_e32 v188, v188
	v_rsq_f32_e32 v189, v189
	v_rsq_f32_e32 v190, v190
	v_rsq_f32_e32 v191, v191
	v_mul_f32_e32 v152, 0xbfb8aa3b, v184
	v_mul_f32_e32 v156, 0xbfb8aa3b, v185
	v_mul_f32_e32 v160, 0xbfb8aa3b, v186
	v_mul_f32_e32 v164, 0xbfb8aa3b, v187
	v_mul_f32_e32 v168, 0xbfb8aa3b, v188
	v_mul_f32_e32 v172, 0xbfb8aa3b, v189
	v_mul_f32_e32 v176, 0xbfb8aa3b, v190
	v_mul_f32_e32 v180, 0xbfb8aa3b, v191
	v_mul_f32_e32 v154, v184, v184
	v_mul_f32_e32 v158, v185, v185
	v_mul_f32_e32 v162, v186, v186
	v_mul_f32_e32 v166, v187, v187
	v_mul_f32_e32 v170, v188, v188
	v_mul_f32_e32 v174, v189, v189
	v_mul_f32_e32 v178, v190, v190
	v_mul_f32_e32 v182, v191, v191
	v_pk_mul_f32 v[124:125], v[120:121], v[124:125]
	v_pk_mul_f32 v[126:127], v[122:123], v[126:127]
	v_pk_mul_f32 v[116:117], v[112:113], v[116:117]
	v_pk_mul_f32 v[118:119], v[114:115], v[118:119]
	v_pk_mul_f32 v[120:121], v[120:121], v[152:153] op_sel_hi:[1,0]
	v_pk_mul_f32 v[122:123], v[122:123], v[152:153] op_sel_hi:[1,0]
	v_pk_mul_f32 v[112:113], v[112:113], v[152:153] op_sel_hi:[1,0]
	v_pk_mul_f32 v[114:115], v[114:115], v[152:153] op_sel_hi:[1,0]
	v_exp_f32_e32 v120, v120
	v_exp_f32_e32 v121, v121
	v_exp_f32_e32 v122, v122
	v_exp_f32_e32 v123, v123
	v_exp_f32_e32 v112, v112
	v_exp_f32_e32 v113, v113
	v_exp_f32_e32 v114, v114
	v_exp_f32_e32 v115, v115
	v_add_f32_e32 v120, 1.0, v120
	v_add_f32_e32 v121, 1.0, v121
	v_add_f32_e32 v122, 1.0, v122
	v_add_f32_e32 v123, 1.0, v123
	v_add_f32_e32 v112, 1.0, v112
	v_add_f32_e32 v113, 1.0, v113
	v_add_f32_e32 v114, 1.0, v114
	v_add_f32_e32 v115, 1.0, v115
	v_rcp_f32_e32 v120, v120
	v_pk_mul_f32 v[108:109], v[104:105], v[108:109]
	v_rcp_f32_e32 v121, v121
	v_pk_mul_f32 v[110:111], v[106:107], v[110:111]
	v_rcp_f32_e32 v122, v122
	v_pk_mul_f32 v[100:101], v[96:97], v[100:101]
; __device__ __forceinline__ unsigned cvt_pk_bf16(float lo, float hi) { unsigned r; asm volatile("v_cvt_pk_bf16_f32 %0, %1, %2" : "=v"(r) : "v"(lo), "v"(hi)); return r; }
; __device__ __forceinline__ float fast_sigmoid(float x) { return __builtin_amdgcn_rcpf(1.0f + __expf(-x)); }
;     __device__ __forceinline__ void operator()(const f32x4 (&acc)[2][2][4][2], const pg8::Unit& u, int wr, int wc, int fr_, int fq_, LAS const unsigned char* xl) const {
;     ...
;                         bf16_t* rowp = O + (size_t)row * ldc + u.pn * 128 + wc * 32 + 8 * fq;
;                         float a[8];
; #pragma unroll
;                         for (int n = 0; n < 2; ++n)
; #pragma unroll
;                             for (int j = 0; j < 4; ++j) { const float g = acc[ai][0][m][n][j] * rinv, up = acc[ai][1][m][n][j] * rinv; a[4 * n + j] = g * fast_sigmoid(g) * up; }
;                         u32x4 w; w.x = pg8::cvt_pk_bf16(a[0], a[1]); w.y = pg8::cvt_pk_bf16(a[2], a[3]); w.z = pg8::cvt_pk_bf16(a[4], a[5]); w.w = pg8::cvt_pk_bf16(a[6], a[7]);
;                         *(u32x4*)rowp = w;
	v_rcp_f32_e32 v123, v123
	v_pk_mul_f32 v[102:103], v[98:99], v[102:103]
	v_rcp_f32_e32 v112, v112
	v_pk_mul_f32 v[104:105], v[104:105], v[156:157] op_sel_hi:[1,0]
	v_rcp_f32_e32 v113, v113
	v_pk_mul_f32 v[106:107], v[106:107], v[156:157] op_sel_hi:[1,0]
	v_rcp_f32_e32 v114, v114
	v_pk_mul_f32 v[96:97], v[96:97], v[156:157] op_sel_hi:[1,0]
	v_rcp_f32_e32 v115, v115
	v_pk_mul_f32 v[98:99], v[98:99], v[156:157] op_sel_hi:[1,0]
	v_exp_f32_e32 v104, v104
	v_pk_mul_f32 v[124:125], v[124:125], v[154:155] op_sel_hi:[1,0]
	v_exp_f32_e32 v105, v105
	v_pk_mul_f32 v[126:127], v[126:127], v[154:155] op_sel_hi:[1,0]
	v_pk_mul_f32 v[116:117], v[116:117], v[154:155] op_sel_hi:[1,0]
	v_exp_f32_e32 v106, v106
	v_pk_mul_f32 v[118:119], v[118:119], v[154:155] op_sel_hi:[1,0]
	v_lshl_add_u64 v[150:151], v[148:149], 0, s[100:101]
	v_exp_f32_e32 v107, v107
	v_pk_mul_f32 v[124:125], v[124:125], v[120:121]
	v_pk_mul_f32 v[126:127], v[126:127], v[122:123]
	v_exp_f32_e32 v96, v96
	v_pk_mul_f32 v[116:117], v[116:117], v[112:113]
	v_pk_mul_f32 v[118:119], v[118:119], v[114:115]
	v_exp_f32_e32 v97, v97
	s_nop 0
	v_cvt_pk_bf16_f32 v136, v124, v125
	v_exp_f32_e32 v98, v98
	v_cvt_pk_bf16_f32 v137, v126, v127
	v_cvt_pk_bf16_f32 v138, v116, v117
	v_exp_f32_e32 v99, v99
	v_cvt_pk_bf16_f32 v139, v118, v119
	global_store_dwordx4 v[148:149], v[136:139], off
	v_add_f32_e32 v104, 1.0, v104
	v_add_f32_e32 v105, 1.0, v105
	v_add_f32_e32 v106, 1.0, v106
	v_add_f32_e32 v107, 1.0, v107
	v_add_f32_e32 v96, 1.0, v96
	v_add_f32_e32 v97, 1.0, v97
	v_add_f32_e32 v98, 1.0, v98
	v_add_f32_e32 v99, 1.0, v99
	v_rcp_f32_e32 v104, v104
	v_pk_mul_f32 v[92:93], v[88:89], v[92:93]
	v_rcp_f32_e32 v105, v105
	v_pk_mul_f32 v[94:95], v[90:91], v[94:95]
	v_rcp_f32_e32 v106, v106
	v_pk_mul_f32 v[84:85], v[80:81], v[84:85]
	v_rcp_f32_e32 v107, v107
	v_pk_mul_f32 v[86:87], v[82:83], v[86:87]
	v_rcp_f32_e32 v96, v96
	v_pk_mul_f32 v[88:89], v[88:89], v[160:161] op_sel_hi:[1,0]
	v_rcp_f32_e32 v97, v97
	v_pk_mul_f32 v[90:91], v[90:91], v[160:161] op_sel_hi:[1,0]
	v_rcp_f32_e32 v98, v98
	v_pk_mul_f32 v[80:81], v[80:81], v[160:161] op_sel_hi:[1,0]
	v_rcp_f32_e32 v99, v99
	v_pk_mul_f32 v[82:83], v[82:83], v[160:161] op_sel_hi:[1,0]
	v_exp_f32_e32 v88, v88
	v_pk_mul_f32 v[108:109], v[108:109], v[158:159] op_sel_hi:[1,0]
	v_exp_f32_e32 v89, v89
	v_pk_mul_f32 v[110:111], v[110:111], v[158:159] op_sel_hi:[1,0]
	v_pk_mul_f32 v[100:101], v[100:101], v[158:159] op_sel_hi:[1,0]
	v_exp_f32_e32 v90, v90
	v_pk_mul_f32 v[102:103], v[102:103], v[158:159] op_sel_hi:[1,0]
	v_lshl_add_u64 v[148:149], v[150:151], 0, s[100:101]
	v_exp_f32_e32 v91, v91
	v_pk_mul_f32 v[108:109], v[108:109], v[104:105]
	v_pk_mul_f32 v[110:111], v[110:111], v[106:107]
	v_exp_f32_e32 v80, v80
	v_pk_mul_f32 v[100:101], v[100:101], v[96:97]
	v_pk_mul_f32 v[102:103], v[102:103], v[98:99]
	v_exp_f32_e32 v81, v81
	s_nop 0
	v_cvt_pk_bf16_f32 v140, v108, v109
	v_exp_f32_e32 v82, v82
	v_cvt_pk_bf16_f32 v141, v110, v111
	v_cvt_pk_bf16_f32 v142, v100, v101
	v_exp_f32_e32 v83, v83
	v_cvt_pk_bf16_f32 v143, v102, v103
	global_store_dwordx4 v[150:151], v[140:143], off
	v_add_f32_e32 v88, 1.0, v88
	v_add_f32_e32 v89, 1.0, v89
	v_add_f32_e32 v90, 1.0, v90
	v_add_f32_e32 v91, 1.0, v91
	v_add_f32_e32 v80, 1.0, v80
	v_add_f32_e32 v81, 1.0, v81
	v_add_f32_e32 v82, 1.0, v82
	v_add_f32_e32 v83, 1.0, v83
	v_rcp_f32_e32 v88, v88
	v_pk_mul_f32 v[76:77], v[72:73], v[76:77]
	v_rcp_f32_e32 v89, v89
	v_pk_mul_f32 v[78:79], v[74:75], v[78:79]
	v_rcp_f32_e32 v90, v90
	v_pk_mul_f32 v[68:69], v[64:65], v[68:69]
	v_rcp_f32_e32 v91, v91
	v_pk_mul_f32 v[70:71], v[66:67], v[70:71]
	v_rcp_f32_e32 v80, v80
	v_pk_mul_f32 v[72:73], v[72:73], v[164:165] op_sel_hi:[1,0]
	v_rcp_f32_e32 v81, v81
	v_pk_mul_f32 v[74:75], v[74:75], v[164:165] op_sel_hi:[1,0]
	v_rcp_f32_e32 v82, v82
	v_pk_mul_f32 v[64:65], v[64:65], v[164:165] op_sel_hi:[1,0]
	v_rcp_f32_e32 v83, v83
	v_pk_mul_f32 v[66:67], v[66:67], v[164:165] op_sel_hi:[1,0]
	v_exp_f32_e32 v72, v72
	v_pk_mul_f32 v[92:93], v[92:93], v[162:163] op_sel_hi:[1,0]
	v_exp_f32_e32 v73, v73
	v_pk_mul_f32 v[94:95], v[94:95], v[162:163] op_sel_hi:[1,0]
	v_pk_mul_f32 v[84:85], v[84:85], v[162:163] op_sel_hi:[1,0]
	v_exp_f32_e32 v74, v74
	v_pk_mul_f32 v[86:87], v[86:87], v[162:163] op_sel_hi:[1,0]
	v_lshl_add_u64 v[150:151], v[148:149], 0, s[100:101]
	v_exp_f32_e32 v75, v75
	v_pk_mul_f32 v[92:93], v[92:93], v[88:89]
	v_pk_mul_f32 v[94:95], v[94:95], v[90:91]
	v_exp_f32_e32 v64, v64
	v_pk_mul_f32 v[84:85], v[84:85], v[80:81]
	v_pk_mul_f32 v[86:87], v[86:87], v[82:83]
	v_exp_f32_e32 v65, v65
	s_nop 0
	v_cvt_pk_bf16_f32 v136, v92, v93
	v_exp_f32_e32 v66, v66
	v_cvt_pk_bf16_f32 v137, v94, v95
	v_cvt_pk_bf16_f32 v138, v84, v85
	v_exp_f32_e32 v67, v67
	v_cvt_pk_bf16_f32 v139, v86, v87
	global_store_dwordx4 v[148:149], v[136:139], off
	v_add_f32_e32 v72, 1.0, v72
	v_add_f32_e32 v73, 1.0, v73
	v_add_f32_e32 v74, 1.0, v74
	v_add_f32_e32 v75, 1.0, v75
	v_add_f32_e32 v64, 1.0, v64
	v_add_f32_e32 v65, 1.0, v65
	v_add_f32_e32 v66, 1.0, v66
	v_add_f32_e32 v67, 1.0, v67
	v_rcp_f32_e32 v72, v72
	v_pk_mul_f32 v[60:61], v[56:57], v[60:61]
	v_rcp_f32_e32 v73, v73
	v_pk_mul_f32 v[62:63], v[58:59], v[62:63]
	v_rcp_f32_e32 v74, v74
	v_pk_mul_f32 v[52:53], v[48:49], v[52:53]
	v_rcp_f32_e32 v75, v75
	v_pk_mul_f32 v[54:55], v[50:51], v[54:55]
	v_rcp_f32_e32 v64, v64
	v_pk_mul_f32 v[56:57], v[56:57], v[168:169] op_sel_hi:[1,0]
	v_rcp_f32_e32 v65, v65
	v_pk_mul_f32 v[58:59], v[58:59], v[168:169] op_sel_hi:[1,0]
	v_rcp_f32_e32 v66, v66
	v_pk_mul_f32 v[48:49], v[48:49], v[168:169] op_sel_hi:[1,0]
	v_rcp_f32_e32 v67, v67
	v_pk_mul_f32 v[50:51], v[50:51], v[168:169] op_sel_hi:[1,0]
; __device__ __forceinline__ unsigned cvt_pk_bf16(float lo, float hi) { unsigned r; asm volatile("v_cvt_pk_bf16_f32 %0, %1, %2" : "=v"(r) : "v"(lo), "v"(hi)); return r; }
; __device__ __forceinline__ float fast_sigmoid(float x) { return __builtin_amdgcn_rcpf(1.0f + __expf(-x)); }
;     __device__ __forceinline__ void operator()(const f32x4 (&acc)[2][2][4][2], const pg8::Unit& u, int wr, int wc, int fr_, int fq_, LAS const unsigned char* xl) const {
;     ...
;                         bf16_t* rowp = O + (size_t)row * ldc + u.pn * 128 + wc * 32 + 8 * fq;
;                         float a[8];
; #pragma unroll
;                         for (int n = 0; n < 2; ++n)
; #pragma unroll
;                             for (int j = 0; j < 4; ++j) { const float g = acc[ai][0][m][n][j] * rinv, up = acc[ai][1][m][n][j] * rinv; a[4 * n + j] = g * fast_sigmoid(g) * up; }
;                         u32x4 w; w.x = pg8::cvt_pk_bf16(a[0], a[1]); w.y = pg8::cvt_pk_bf16(a[2], a[3]); w.z = pg8::cvt_pk_bf16(a[4], a[5]); w.w = pg8::cvt_pk_bf16(a[6], a[7]);
;                         *(u32x4*)rowp = w;
	v_exp_f32_e32 v56, v56
	v_pk_mul_f32 v[76:77], v[76:77], v[166:167] op_sel_hi:[1,0]
	v_exp_f32_e32 v57, v57
	v_pk_mul_f32 v[78:79], v[78:79], v[166:167] op_sel_hi:[1,0]
	v_pk_mul_f32 v[68:69], v[68:69], v[166:167] op_sel_hi:[1,0]
	v_exp_f32_e32 v58, v58
	v_pk_mul_f32 v[70:71], v[70:71], v[166:167] op_sel_hi:[1,0]
	v_lshl_add_u64 v[148:149], v[150:151], 0, s[0:1]
	v_exp_f32_e32 v59, v59
	v_pk_mul_f32 v[76:77], v[76:77], v[72:73]
	v_pk_mul_f32 v[78:79], v[78:79], v[74:75]
	v_exp_f32_e32 v48, v48
	v_pk_mul_f32 v[68:69], v[68:69], v[64:65]
	v_pk_mul_f32 v[70:71], v[70:71], v[66:67]
	v_exp_f32_e32 v49, v49
	s_nop 0
	v_cvt_pk_bf16_f32 v140, v76, v77
	v_exp_f32_e32 v50, v50
	v_cvt_pk_bf16_f32 v141, v78, v79
	v_cvt_pk_bf16_f32 v142, v68, v69
	v_exp_f32_e32 v51, v51
	v_cvt_pk_bf16_f32 v143, v70, v71
	global_store_dwordx4 v[150:151], v[140:143], off
	v_add_f32_e32 v56, 1.0, v56
	v_add_f32_e32 v57, 1.0, v57
	v_add_f32_e32 v58, 1.0, v58
	v_add_f32_e32 v59, 1.0, v59
	v_add_f32_e32 v48, 1.0, v48
	v_add_f32_e32 v49, 1.0, v49
	v_add_f32_e32 v50, 1.0, v50
	v_add_f32_e32 v51, 1.0, v51
	v_rcp_f32_e32 v56, v56
	v_pk_mul_f32 v[44:45], v[40:41], v[44:45]
	v_rcp_f32_e32 v57, v57
	v_pk_mul_f32 v[46:47], v[42:43], v[46:47]
	v_rcp_f32_e32 v58, v58
	v_pk_mul_f32 v[36:37], v[32:33], v[36:37]
	v_rcp_f32_e32 v59, v59
	v_pk_mul_f32 v[38:39], v[34:35], v[38:39]
	v_rcp_f32_e32 v48, v48
	v_pk_mul_f32 v[40:41], v[40:41], v[172:173] op_sel_hi:[1,0]
	v_rcp_f32_e32 v49, v49
	v_pk_mul_f32 v[42:43], v[42:43], v[172:173] op_sel_hi:[1,0]
	v_rcp_f32_e32 v50, v50
	v_pk_mul_f32 v[32:33], v[32:33], v[172:173] op_sel_hi:[1,0]
	v_rcp_f32_e32 v51, v51
	v_pk_mul_f32 v[34:35], v[34:35], v[172:173] op_sel_hi:[1,0]
	v_exp_f32_e32 v40, v40
	v_pk_mul_f32 v[60:61], v[60:61], v[170:171] op_sel_hi:[1,0]
	v_exp_f32_e32 v41, v41
	v_pk_mul_f32 v[62:63], v[62:63], v[170:171] op_sel_hi:[1,0]
	v_pk_mul_f32 v[52:53], v[52:53], v[170:171] op_sel_hi:[1,0]
	v_exp_f32_e32 v42, v42
	v_pk_mul_f32 v[54:55], v[54:55], v[170:171] op_sel_hi:[1,0]
	v_lshl_add_u64 v[150:151], v[148:149], 0, s[100:101]
	v_exp_f32_e32 v43, v43
	v_pk_mul_f32 v[60:61], v[60:61], v[56:57]
	v_pk_mul_f32 v[62:63], v[62:63], v[58:59]
	v_exp_f32_e32 v32, v32
	v_pk_mul_f32 v[52:53], v[52:53], v[48:49]
	v_pk_mul_f32 v[54:55], v[54:55], v[50:51]
	v_exp_f32_e32 v33, v33
	s_nop 0
	v_cvt_pk_bf16_f32 v136, v60, v61
	v_exp_f32_e32 v34, v34
	v_cvt_pk_bf16_f32 v137, v62, v63
	v_cvt_pk_bf16_f32 v138, v52, v53
	v_exp_f32_e32 v35, v35
	v_cvt_pk_bf16_f32 v139, v54, v55
	global_store_dwordx4 v[148:149], v[136:139], off
	v_add_f32_e32 v40, 1.0, v40
	v_add_f32_e32 v41, 1.0, v41
	v_add_f32_e32 v42, 1.0, v42
	v_add_f32_e32 v43, 1.0, v43
	v_add_f32_e32 v32, 1.0, v32
	v_add_f32_e32 v33, 1.0, v33
	v_add_f32_e32 v34, 1.0, v34
	v_add_f32_e32 v35, 1.0, v35
	v_rcp_f32_e32 v40, v40
	v_pk_mul_f32 v[28:29], v[24:25], v[28:29]
	v_rcp_f32_e32 v41, v41
	v_pk_mul_f32 v[30:31], v[26:27], v[30:31]
	v_rcp_f32_e32 v42, v42
	v_pk_mul_f32 v[20:21], v[16:17], v[20:21]
	v_rcp_f32_e32 v43, v43
	v_pk_mul_f32 v[22:23], v[18:19], v[22:23]
	v_rcp_f32_e32 v32, v32
	v_pk_mul_f32 v[24:25], v[24:25], v[176:177] op_sel_hi:[1,0]
	v_rcp_f32_e32 v33, v33
	v_pk_mul_f32 v[26:27], v[26:27], v[176:177] op_sel_hi:[1,0]
	v_rcp_f32_e32 v34, v34
	v_pk_mul_f32 v[16:17], v[16:17], v[176:177] op_sel_hi:[1,0]
	v_rcp_f32_e32 v35, v35
	v_pk_mul_f32 v[18:19], v[18:19], v[176:177] op_sel_hi:[1,0]
	v_exp_f32_e32 v24, v24
	v_pk_mul_f32 v[44:45], v[44:45], v[174:175] op_sel_hi:[1,0]
	v_exp_f32_e32 v25, v25
	v_pk_mul_f32 v[46:47], v[46:47], v[174:175] op_sel_hi:[1,0]
	v_pk_mul_f32 v[36:37], v[36:37], v[174:175] op_sel_hi:[1,0]
	v_exp_f32_e32 v26, v26
	v_pk_mul_f32 v[38:39], v[38:39], v[174:175] op_sel_hi:[1,0]
	v_lshl_add_u64 v[148:149], v[150:151], 0, s[100:101]
	v_exp_f32_e32 v27, v27
	v_pk_mul_f32 v[44:45], v[44:45], v[40:41]
	v_pk_mul_f32 v[46:47], v[46:47], v[42:43]
	v_exp_f32_e32 v16, v16
	v_pk_mul_f32 v[36:37], v[36:37], v[32:33]
	v_pk_mul_f32 v[38:39], v[38:39], v[34:35]
	v_exp_f32_e32 v17, v17
	s_nop 0
	v_cvt_pk_bf16_f32 v140, v44, v45
	v_exp_f32_e32 v18, v18
	v_cvt_pk_bf16_f32 v141, v46, v47
	v_cvt_pk_bf16_f32 v142, v36, v37
	v_exp_f32_e32 v19, v19
	v_cvt_pk_bf16_f32 v143, v38, v39
	global_store_dwordx4 v[150:151], v[140:143], off
	v_add_f32_e32 v24, 1.0, v24
	v_add_f32_e32 v25, 1.0, v25
	v_add_f32_e32 v26, 1.0, v26
	v_add_f32_e32 v27, 1.0, v27
	v_add_f32_e32 v16, 1.0, v16
	v_add_f32_e32 v17, 1.0, v17
	v_add_f32_e32 v18, 1.0, v18
	v_add_f32_e32 v19, 1.0, v19
	v_rcp_f32_e32 v24, v24
	v_pk_mul_f32 v[12:13], v[8:9], v[12:13]
	v_rcp_f32_e32 v25, v25
	v_pk_mul_f32 v[14:15], v[10:11], v[14:15]
	v_rcp_f32_e32 v26, v26
	v_pk_mul_f32 v[0:1], v[4:5], v[0:1]
	v_rcp_f32_e32 v27, v27
	v_pk_mul_f32 v[2:3], v[6:7], v[2:3]
	v_rcp_f32_e32 v16, v16
	v_pk_mul_f32 v[8:9], v[8:9], v[180:181] op_sel_hi:[1,0]
	v_rcp_f32_e32 v17, v17
	v_pk_mul_f32 v[10:11], v[10:11], v[180:181] op_sel_hi:[1,0]
	v_rcp_f32_e32 v18, v18
	v_pk_mul_f32 v[4:5], v[4:5], v[180:181] op_sel_hi:[1,0]
	v_rcp_f32_e32 v19, v19
	v_pk_mul_f32 v[6:7], v[6:7], v[180:181] op_sel_hi:[1,0]
	v_exp_f32_e32 v8, v8
	v_pk_mul_f32 v[28:29], v[28:29], v[178:179] op_sel_hi:[1,0]
	v_exp_f32_e32 v9, v9
	v_pk_mul_f32 v[30:31], v[30:31], v[178:179] op_sel_hi:[1,0]
	v_pk_mul_f32 v[20:21], v[20:21], v[178:179] op_sel_hi:[1,0]
	v_exp_f32_e32 v10, v10
	v_pk_mul_f32 v[22:23], v[22:23], v[178:179] op_sel_hi:[1,0]
	v_lshl_add_u64 v[150:151], v[148:149], 0, s[100:101]
	v_exp_f32_e32 v11, v11
	v_pk_mul_f32 v[28:29], v[28:29], v[24:25]
	v_pk_mul_f32 v[30:31], v[30:31], v[26:27]
	v_exp_f32_e32 v4, v4
	v_pk_mul_f32 v[20:21], v[20:21], v[16:17]
	v_pk_mul_f32 v[22:23], v[22:23], v[18:19]
	v_exp_f32_e32 v5, v5
	s_nop 0
	v_cvt_pk_bf16_f32 v136, v28, v29
	v_exp_f32_e32 v6, v6
	v_cvt_pk_bf16_f32 v137, v30, v31
	v_cvt_pk_bf16_f32 v138, v20, v21
	v_exp_f32_e32 v7, v7
	v_cvt_pk_bf16_f32 v139, v22, v23
	global_store_dwordx4 v[148:149], v[136:139], off
	v_add_f32_e32 v8, 1.0, v8
	v_add_f32_e32 v9, 1.0, v9
	v_add_f32_e32 v10, 1.0, v10
	v_add_f32_e32 v11, 1.0, v11
	v_add_f32_e32 v4, 1.0, v4
	v_add_f32_e32 v5, 1.0, v5
	v_add_f32_e32 v6, 1.0, v6
	v_add_f32_e32 v7, 1.0, v7
	v_rcp_f32_e32 v8, v8
	v_rcp_f32_e32 v9, v9
	v_rcp_f32_e32 v10, v10
	v_rcp_f32_e32 v11, v11
	v_rcp_f32_e32 v4, v4
	v_rcp_f32_e32 v5, v5
	v_rcp_f32_e32 v6, v6
	v_rcp_f32_e32 v7, v7
	v_pk_mul_f32 v[12:13], v[12:13], v[182:183] op_sel_hi:[1,0]
	v_pk_mul_f32 v[14:15], v[14:15], v[182:183] op_sel_hi:[1,0]
	v_pk_mul_f32 v[0:1], v[0:1], v[182:183] op_sel_hi:[1,0]
	v_pk_mul_f32 v[2:3], v[2:3], v[182:183] op_sel_hi:[1,0]
	v_pk_mul_f32 v[12:13], v[12:13], v[8:9]
	v_pk_mul_f32 v[14:15], v[14:15], v[10:11]
	v_pk_mul_f32 v[0:1], v[0:1], v[4:5]
	v_pk_mul_f32 v[2:3], v[2:3], v[6:7]
	s_nop 0
	v_cvt_pk_bf16_f32 v140, v12, v13
	v_cvt_pk_bf16_f32 v141, v14, v15
	v_cvt_pk_bf16_f32 v142, v0, v1
	v_cvt_pk_bf16_f32 v143, v2, v3
	global_store_dwordx4 v[150:151], v[140:143], off
	s_mov_b64 s[0:1], -1
	s_cbranch_vccnz .LBB0_403
	s_andn2_b64 vcc, exec, s[20:21]
	s_cbranch_vccnz .LBB0_402
	s_barrier
	s_branch .LBB0_402
